# GEMM unit switch: the wr==1 realignment barrier moved behind the next-unit scheduling code (half 1 computes S.next while it would wait anyway), on top of the prio shift + peel
# baseline (speedup 1.0000x reference)
; #define PG8_STAGE(bufoff, gbase, voff) do { _Pragma("unroll") for (int _i = 0; _i < 2; ++_i) \
;         __builtin_amdgcn_global_load_lds((const unsigned*)((const char*)(gbase) + (voff)[_i]), (LAS unsigned*)(lds + (bufoff) + ldsw + _i * 8192), 16, 0, 0); } while (0)
; #define PG8_LDA(dst, b, h) do { _Pragma("unroll") for (int m = 0; m < 4; ++m) _Pragma("unroll") for (int k = 0; k < 2; ++k) dst[m][k] = *(const LAS bf16x8*)(lds + PG8_SA(b, h) + aoff + m * 2048 + k * 1024); } while (0)
; #define PG8_LDB(dst, b, h) do { _Pragma("unroll") for (int n = 0; n < 2; ++n) _Pragma("unroll") for (int k = 0; k < 2; ++k) dst[n][k] = *(const LAS bf16x8*)(lds + PG8_SB(b, h) + boff + n * 2048 + k * 1024); } while (0)
; #define PG8_MMA(ai, bj, At, Bt) do { __builtin_amdgcn_s_setprio(1); _Pragma("unroll") for (int m = 0; m < 4; ++m) _Pragma("unroll") for (int n = 0; n < 2; ++n) _Pragma("unroll") for (int k = 0; k < 2; ++k) \
;         acc[ai][bj][m][n] = __builtin_amdgcn_mfma_f32_16x16x32_bf16(Bt[n][k], At[m][k], acc[ai][bj][m][n], 0, 0, 0); __builtin_amdgcn_s_setprio(0); } while (0)
; #define PG8_WAIT_V(n) asm volatile("s_waitcnt vmcnt(" #n ")" ::: "memory")
; #define PG8_WAIT_L(n) asm volatile("s_waitcnt lgkmcnt(" #n ")" ::: "memory")
; #define PG8_BAR __builtin_amdgcn_s_barrier()
; #define PG8_SCHED __builtin_amdgcn_sched_barrier(0)
; __device__ __forceinline__ void gemm_phase(const int tid, LAS unsigned char* lds, const Gemm g, const StaticOrder& S, const int mode  , void* Cout, const int ldc, float* rvs, const float* rbs, const float* rbs_tail) {
;     ...
;         const bool has_next = S.next(ui + 1, nxt);
;         const char* nA = has_next ? PG8_UA(nxt) : cA; const char* nB = has_next ? PG8_UB(nxt) : cB;
;         const int ntu = cur.kc < 0 ? nt : 8;
;         for (int t = 0; t < ntu; t += 2) {
;             const bool last = (t == ntu - 2);
;             const char* a1 = cA + (size_t)(t + 1) * kstep;
;             const char* a2 = last ? nA : cA + (size_t)(t + 2) * kstep; const char* b2 = last ? nB : cB + (size_t)(t + 2) * kstep;
;             const char* a3 = a2 + kstep; const char* b3 = b2 + kstep;
;             PG8_LDB(B0, 0, 0); PG8_LDB(B1, 0, 1); PG8_SCHED; PG8_LDA(At, 0, 0); PG8_STAGE(PG8_SA(1, 1), a1 + hstepA, voffA);
;             PG8_WAIT_V(8); PG8_WAIT_L(0); PG8_BAR; PG8_MMA(0, 0, At, B0); PG8_MMA(0, 1, At, B1); PG8_BAR; PG8_SCHED;
;     ...
;         if (wr == 1) PG8_BAR;
.LBB0_230:
	s_cmp_lt_i32 s44, 0
	s_cselect_b64 s[24:25], -1, 0
	s_and_b64 s[72:73], s[24:25], exec
	s_cselect_b32 s3, s48, 8
	s_add_i32 s33, s3, -2
	s_add_u32 s60, s60, 0x80
	s_addc_u32 s61, s61, 0
	s_add_u32 s45, s62, 0x100
	s_mov_b32 s68, 0
	s_addc_u32 s53, s63, 0
	s_waitcnt vmcnt(0)
	s_waitcnt lgkmcnt(0)
	s_cmp_lt_u32 s17, 2
	s_cbranch_scc1 .Lgemm_nobar
	s_andn2_b64 vcc, exec, s[92:93]
	s_cbranch_vccnz .Lgemm_nobar
	s_barrier
.Lgemm_nobar:
.Lgemm_peel:
	s_add_i32 s72, s68, 2
	s_add_u32 s62, s60, 0x80
	s_addc_u32 s63, s61, 0
	s_add_i32 s73, 0, 0x10000
	s_cmp_eq_u32 s33, s68
	s_cselect_b32 s63, s55, s63
	s_cselect_b32 s62, s54, s62
	v_add_u32_e32 v158, s73, v147
	s_cselect_b32 s75, s57, s53
	s_cselect_b32 s74, s56, s45
	s_add_i32 s68, 0, 0x14000
	ds_read_b128 v[142:145], v158
	ds_read_b128 v[150:153], v158 offset:1024
	ds_read_b128 v[154:157], v158 offset:2048
	ds_read_b128 v[168:171], v158 offset:3072
	v_add_u32_e32 v158, s68, v147
	ds_read_b128 v[172:175], v158
	ds_read_b128 v[176:179], v158 offset:1024
	ds_read_b128 v[180:183], v158 offset:2048
	ds_read_b128 v[184:187], v158 offset:3072
	v_lshl_add_u64 v[158:159], s[60:61], 0, v[138:139]
	s_add_i32 m0, s71, 0xc000
	ds_read_b128 v[188:191], v149
	ds_read_b128 v[212:215], v149 offset:1024
	ds_read_b128 v[216:219], v149 offset:2048
	ds_read_b128 v[220:223], v149 offset:3072
	ds_read_b128 v[224:227], v149 offset:4096
	ds_read_b128 v[228:231], v149 offset:5120
	ds_read_b128 v[232:235], v149 offset:6144
	ds_read_b128 v[236:239], v149 offset:7168
	global_load_lds_dwordx4 v[158:159], off
	v_lshl_add_u64 v[158:159], s[60:61], 0, v[140:141]
	s_add_i32 m0, s71, 0xe000
	s_nop 0
	global_load_lds_dwordx4 v[158:159], off
	s_setprio 1
	s_waitcnt vmcnt(8)
	s_waitcnt lgkmcnt(0)
	s_barrier
	s_waitcnt lgkmcnt(0)
	v_mfma_f32_16x16x32_bf16 v[124:127], v[142:145], v[188:191], 0
	v_mfma_f32_16x16x32_bf16 v[120:123], v[154:157], v[188:191], 0
	v_mfma_f32_16x16x32_bf16 v[116:119], v[142:145], v[216:219], 0
	v_mfma_f32_16x16x32_bf16 v[112:115], v[154:157], v[216:219], 0
	v_mfma_f32_16x16x32_bf16 v[104:107], v[142:145], v[224:227], 0
	v_mfma_f32_16x16x32_bf16 v[96:99], v[154:157], v[224:227], 0
	v_mfma_f32_16x16x32_bf16 v[88:91], v[142:145], v[232:235], 0
	v_mfma_f32_16x16x32_bf16 v[80:83], v[154:157], v[232:235], 0
	v_mfma_f32_16x16x32_bf16 v[124:127], v[150:153], v[212:215], v[124:127]
	v_mfma_f32_16x16x32_bf16 v[120:123], v[168:171], v[212:215], v[120:123]
	v_mfma_f32_16x16x32_bf16 v[116:119], v[150:153], v[220:223], v[116:119]
	v_mfma_f32_16x16x32_bf16 v[112:115], v[168:171], v[220:223], v[112:115]
	v_mfma_f32_16x16x32_bf16 v[104:107], v[150:153], v[228:231], v[104:107]
	v_mfma_f32_16x16x32_bf16 v[96:99], v[168:171], v[228:231], v[96:99]
	v_mfma_f32_16x16x32_bf16 v[88:91], v[150:153], v[236:239], v[88:91]
	v_mfma_f32_16x16x32_bf16 v[80:83], v[168:171], v[236:239], v[80:83]
	s_setprio 0
	s_setprio 1
	v_mfma_f32_16x16x32_bf16 v[108:111], v[172:175], v[188:191], 0
	v_mfma_f32_16x16x32_bf16 v[100:103], v[180:183], v[188:191], 0
	v_mfma_f32_16x16x32_bf16 v[92:95], v[172:175], v[216:219], 0
	v_mfma_f32_16x16x32_bf16 v[84:87], v[180:183], v[216:219], 0
	v_mfma_f32_16x16x32_bf16 v[76:79], v[172:175], v[224:227], 0
	v_mfma_f32_16x16x32_bf16 v[72:75], v[180:183], v[224:227], 0
	v_mfma_f32_16x16x32_bf16 v[68:71], v[172:175], v[232:235], 0
	v_mfma_f32_16x16x32_bf16 v[64:67], v[180:183], v[232:235], 0
	v_mfma_f32_16x16x32_bf16 v[108:111], v[176:179], v[212:215], v[108:111]
	v_mfma_f32_16x16x32_bf16 v[100:103], v[184:187], v[212:215], v[100:103]
	v_mfma_f32_16x16x32_bf16 v[92:95], v[176:179], v[220:223], v[92:95]
	v_mfma_f32_16x16x32_bf16 v[84:87], v[184:187], v[220:223], v[84:87]
	v_mfma_f32_16x16x32_bf16 v[76:79], v[176:179], v[228:231], v[76:79]
	v_mfma_f32_16x16x32_bf16 v[72:75], v[184:187], v[228:231], v[72:75]
	v_mfma_f32_16x16x32_bf16 v[68:71], v[176:179], v[236:239], v[68:71]
	v_mfma_f32_16x16x32_bf16 v[64:67], v[184:187], v[236:239], v[64:67]
	s_barrier
	s_setprio 0
	s_add_i32 s73, s73, s70
	v_lshl_add_u64 v[158:159], s[74:75], 0, v[160:161]
	s_mov_b32 m0, s73
	ds_read_b128 v[188:191], v149 offset:16384
	ds_read_b128 v[212:215], v149 offset:17408
	ds_read_b128 v[216:219], v149 offset:18432
	ds_read_b128 v[220:223], v149 offset:19456
	ds_read_b128 v[224:227], v149 offset:20480
	ds_read_b128 v[228:231], v149 offset:21504
	ds_read_b128 v[232:235], v149 offset:22528
	ds_read_b128 v[236:239], v149 offset:23552
	global_load_lds_dwordx4 v[158:159], off
	s_add_i32 m0, s73, 0x2000
	v_lshl_add_u64 v[192:193], s[74:75], 0, v[132:133]
	s_add_u32 s74, s74, s59
	s_addc_u32 s75, s75, 0
	s_add_i32 s68, s68, s70
	global_load_lds_dwordx4 v[192:193], off
	v_lshl_add_u64 v[194:195], s[74:75], 0, v[160:161]
	s_mov_b32 m0, s68
	v_lshl_add_u64 v[240:241], s[74:75], 0, v[132:133]
	global_load_lds_dwordx4 v[194:195], off
	s_add_i32 m0, s68, 0x2000
	v_lshl_add_u64 v[242:243], s[62:63], 0, v[128:129]
	global_load_lds_dwordx4 v[240:241], off
	s_mov_b32 m0, s71
	v_lshl_add_u64 v[244:245], s[62:63], 0, v[130:131]
	global_load_lds_dwordx4 v[242:243], off
	s_mov_b32 m0, s88
	s_nop 0
	global_load_lds_dwordx4 v[244:245], off
	s_setprio 1
	s_waitcnt vmcnt(8)
	s_waitcnt lgkmcnt(0)
	s_barrier
; #define PG8_STAGE(bufoff, gbase, voff) do { _Pragma("unroll") for (int _i = 0; _i < 2; ++_i) \
;         __builtin_amdgcn_global_load_lds((const unsigned*)((const char*)(gbase) + (voff)[_i]), (LAS unsigned*)(lds + (bufoff) + ldsw + _i * 8192), 16, 0, 0); } while (0)
; #define PG8_LDA(dst, b, h) do { _Pragma("unroll") for (int m = 0; m < 4; ++m) _Pragma("unroll") for (int k = 0; k < 2; ++k) dst[m][k] = *(const LAS bf16x8*)(lds + PG8_SA(b, h) + aoff + m * 2048 + k * 1024); } while (0)
; #define PG8_LDB(dst, b, h) do { _Pragma("unroll") for (int n = 0; n < 2; ++n) _Pragma("unroll") for (int k = 0; k < 2; ++k) dst[n][k] = *(const LAS bf16x8*)(lds + PG8_SB(b, h) + boff + n * 2048 + k * 1024); } while (0)
; #define PG8_MMA(ai, bj, At, Bt) do { __builtin_amdgcn_s_setprio(1); _Pragma("unroll") for (int m = 0; m < 4; ++m) _Pragma("unroll") for (int n = 0; n < 2; ++n) _Pragma("unroll") for (int k = 0; k < 2; ++k) \
;         acc[ai][bj][m][n] = __builtin_amdgcn_mfma_f32_16x16x32_bf16(Bt[n][k], At[m][k], acc[ai][bj][m][n], 0, 0, 0); __builtin_amdgcn_s_setprio(0); } while (0)
; #define PG8_WAIT_V(n) asm volatile("s_waitcnt vmcnt(" #n ")" ::: "memory")
; #define PG8_WAIT_L(n) asm volatile("s_waitcnt lgkmcnt(" #n ")" ::: "memory")
; #define PG8_BAR __builtin_amdgcn_s_barrier()
; #define PG8_SCHED __builtin_amdgcn_sched_barrier(0)
; __device__ __forceinline__ void gemm_phase(const int tid, LAS unsigned char* lds, const Gemm g, const StaticOrder& S, const int mode  , void* Cout, const int ldc, float* rvs, const float* rbs, const float* rbs_tail) {
;     ...
;             PG8_WAIT_V(8); PG8_WAIT_L(0); PG8_BAR; PG8_MMA(0, 0, At, B0); PG8_MMA(0, 1, At, B1); PG8_BAR; PG8_SCHED;
;             PG8_LDA(At, 0, 1); PG8_STAGE(PG8_SB(0, 0), b2, voffB); PG8_STAGE(PG8_SB(0, 1), b2 + hstepB, voffB); PG8_STAGE(PG8_SA(0, 0), a2, voffA);
;             PG8_WAIT_V(8); PG8_WAIT_L(0); PG8_BAR; PG8_MMA(1, 0, At, B0); PG8_MMA(1, 1, At, B1); PG8_BAR; PG8_SCHED;
;             PG8_LDB(B0, 1, 0); PG8_LDB(B1, 1, 1); PG8_SCHED; PG8_LDA(At, 1, 0); PG8_STAGE(PG8_SA(0, 1), a2 + hstepA, voffA);
;             PG8_WAIT_V(8); PG8_WAIT_L(0); PG8_BAR; PG8_MMA(0, 0, At, B0); PG8_MMA(0, 1, At, B1); PG8_BAR; PG8_SCHED;
	s_waitcnt lgkmcnt(0)
	v_mfma_f32_16x16x32_bf16 v[60:63], v[142:145], v[188:191], 0
	v_mfma_f32_16x16x32_bf16 v[56:59], v[154:157], v[188:191], 0
	v_mfma_f32_16x16x32_bf16 v[52:55], v[142:145], v[216:219], 0
	v_mfma_f32_16x16x32_bf16 v[48:51], v[154:157], v[216:219], 0
	v_mfma_f32_16x16x32_bf16 v[36:39], v[142:145], v[224:227], 0
	v_mfma_f32_16x16x32_bf16 v[32:35], v[154:157], v[224:227], 0
	v_mfma_f32_16x16x32_bf16 v[20:23], v[142:145], v[232:235], 0
	v_mfma_f32_16x16x32_bf16 v[16:19], v[154:157], v[232:235], 0
	v_mfma_f32_16x16x32_bf16 v[60:63], v[150:153], v[212:215], v[60:63]
	v_mfma_f32_16x16x32_bf16 v[56:59], v[168:171], v[212:215], v[56:59]
	v_mfma_f32_16x16x32_bf16 v[52:55], v[150:153], v[220:223], v[52:55]
	v_mfma_f32_16x16x32_bf16 v[48:51], v[168:171], v[220:223], v[48:51]
	v_mfma_f32_16x16x32_bf16 v[36:39], v[150:153], v[228:231], v[36:39]
	v_mfma_f32_16x16x32_bf16 v[32:35], v[168:171], v[228:231], v[32:35]
	v_mfma_f32_16x16x32_bf16 v[20:23], v[150:153], v[236:239], v[20:23]
	v_mfma_f32_16x16x32_bf16 v[16:19], v[168:171], v[236:239], v[16:19]
	s_setprio 0
	s_setprio 1
	v_mfma_f32_16x16x32_bf16 v[44:47], v[172:175], v[188:191], 0
	v_mfma_f32_16x16x32_bf16 v[40:43], v[180:183], v[188:191], 0
	v_mfma_f32_16x16x32_bf16 v[28:31], v[172:175], v[216:219], 0
	v_mfma_f32_16x16x32_bf16 v[24:27], v[180:183], v[216:219], 0
	v_mfma_f32_16x16x32_bf16 v[12:15], v[172:175], v[224:227], 0
	v_mfma_f32_16x16x32_bf16 v[8:11], v[180:183], v[224:227], 0
	v_mfma_f32_16x16x32_bf16 v[4:7], v[172:175], v[232:235], 0
	v_mfma_f32_16x16x32_bf16 v[0:3], v[180:183], v[232:235], 0
	v_mfma_f32_16x16x32_bf16 v[44:47], v[176:179], v[212:215], v[44:47]
	v_mfma_f32_16x16x32_bf16 v[40:43], v[184:187], v[212:215], v[40:43]
	v_mfma_f32_16x16x32_bf16 v[28:31], v[176:179], v[220:223], v[28:31]
	v_mfma_f32_16x16x32_bf16 v[24:27], v[184:187], v[220:223], v[24:27]
	v_mfma_f32_16x16x32_bf16 v[12:15], v[176:179], v[228:231], v[12:15]
	v_mfma_f32_16x16x32_bf16 v[8:11], v[184:187], v[228:231], v[8:11]
	v_mfma_f32_16x16x32_bf16 v[4:7], v[176:179], v[236:239], v[4:7]
	v_mfma_f32_16x16x32_bf16 v[0:3], v[184:187], v[236:239], v[0:3]
	s_barrier
	s_setprio 0
	s_add_i32 s68, 0, 0x18000
	v_add_u32_e32 v165, s68, v147
	s_add_i32 s73, 0, 0x1c000
	ds_read_b128 v[142:145], v165
	ds_read_b128 v[150:153], v165 offset:1024
	ds_read_b128 v[154:157], v165 offset:2048
	ds_read_b128 v[168:171], v165 offset:3072
	v_add_u32_e32 v165, s73, v147
	ds_read_b128 v[172:175], v165
	ds_read_b128 v[176:179], v165 offset:1024
	ds_read_b128 v[180:183], v165 offset:2048
	ds_read_b128 v[184:187], v165 offset:3072
	s_add_u32 s62, s62, s46
	s_addc_u32 s63, s63, 0
	s_mov_b32 m0, s89
	v_lshl_add_u64 v[246:247], s[62:63], 0, v[128:129]
	ds_read_b128 v[188:191], v149 offset:32768
	ds_read_b128 v[212:215], v149 offset:33792
	ds_read_b128 v[216:219], v149 offset:34816
	ds_read_b128 v[220:223], v149 offset:35840
	ds_read_b128 v[224:227], v149 offset:36864
	ds_read_b128 v[228:231], v149 offset:37888
	ds_read_b128 v[232:235], v149 offset:38912
	ds_read_b128 v[236:239], v149 offset:39936
	global_load_lds_dwordx4 v[246:247], off
	v_lshl_add_u64 v[246:247], s[62:63], 0, v[130:131]
	s_mov_b32 m0, s90
	s_nop 0
	global_load_lds_dwordx4 v[246:247], off
	s_setprio 1
	s_waitcnt vmcnt(8)
	s_waitcnt lgkmcnt(0)
	s_barrier
	s_waitcnt lgkmcnt(0)
	v_mfma_f32_16x16x32_bf16 v[124:127], v[142:145], v[188:191], v[124:127]
	v_mfma_f32_16x16x32_bf16 v[120:123], v[154:157], v[188:191], v[120:123]
	v_mfma_f32_16x16x32_bf16 v[116:119], v[142:145], v[216:219], v[116:119]
	v_mfma_f32_16x16x32_bf16 v[112:115], v[154:157], v[216:219], v[112:115]
	v_mfma_f32_16x16x32_bf16 v[104:107], v[142:145], v[224:227], v[104:107]
	v_mfma_f32_16x16x32_bf16 v[96:99], v[154:157], v[224:227], v[96:99]
	v_mfma_f32_16x16x32_bf16 v[88:91], v[142:145], v[232:235], v[88:91]
	v_mfma_f32_16x16x32_bf16 v[80:83], v[154:157], v[232:235], v[80:83]
	v_mfma_f32_16x16x32_bf16 v[124:127], v[150:153], v[212:215], v[124:127]
	v_mfma_f32_16x16x32_bf16 v[120:123], v[168:171], v[212:215], v[120:123]
	v_mfma_f32_16x16x32_bf16 v[116:119], v[150:153], v[220:223], v[116:119]
	v_mfma_f32_16x16x32_bf16 v[112:115], v[168:171], v[220:223], v[112:115]
	v_mfma_f32_16x16x32_bf16 v[104:107], v[150:153], v[228:231], v[104:107]
	v_mfma_f32_16x16x32_bf16 v[96:99], v[168:171], v[228:231], v[96:99]
	v_mfma_f32_16x16x32_bf16 v[88:91], v[150:153], v[236:239], v[88:91]
	v_mfma_f32_16x16x32_bf16 v[80:83], v[168:171], v[236:239], v[80:83]
	s_setprio 0
	s_setprio 1
	v_mfma_f32_16x16x32_bf16 v[108:111], v[172:175], v[188:191], v[108:111]
	v_mfma_f32_16x16x32_bf16 v[100:103], v[180:183], v[188:191], v[100:103]
	v_mfma_f32_16x16x32_bf16 v[92:95], v[172:175], v[216:219], v[92:95]
	v_mfma_f32_16x16x32_bf16 v[84:87], v[180:183], v[216:219], v[84:87]
	v_mfma_f32_16x16x32_bf16 v[76:79], v[172:175], v[224:227], v[76:79]
	v_mfma_f32_16x16x32_bf16 v[72:75], v[180:183], v[224:227], v[72:75]
	v_mfma_f32_16x16x32_bf16 v[68:71], v[172:175], v[232:235], v[68:71]
	v_mfma_f32_16x16x32_bf16 v[64:67], v[180:183], v[232:235], v[64:67]
	v_mfma_f32_16x16x32_bf16 v[108:111], v[176:179], v[212:215], v[108:111]
	v_mfma_f32_16x16x32_bf16 v[100:103], v[184:187], v[212:215], v[100:103]
	v_mfma_f32_16x16x32_bf16 v[92:95], v[176:179], v[220:223], v[92:95]
	v_mfma_f32_16x16x32_bf16 v[84:87], v[184:187], v[220:223], v[84:87]
	v_mfma_f32_16x16x32_bf16 v[76:79], v[176:179], v[228:231], v[76:79]
	v_mfma_f32_16x16x32_bf16 v[72:75], v[184:187], v[228:231], v[72:75]
	v_mfma_f32_16x16x32_bf16 v[68:71], v[176:179], v[236:239], v[68:71]
	v_mfma_f32_16x16x32_bf16 v[64:67], v[184:187], v[236:239], v[64:67]
	s_barrier
; #define PG8_STAGE(bufoff, gbase, voff) do { _Pragma("unroll") for (int _i = 0; _i < 2; ++_i) \
;         __builtin_amdgcn_global_load_lds((const unsigned*)((const char*)(gbase) + (voff)[_i]), (LAS unsigned*)(lds + (bufoff) + ldsw + _i * 8192), 16, 0, 0); } while (0)
; #define PG8_LDA(dst, b, h) do { _Pragma("unroll") for (int m = 0; m < 4; ++m) _Pragma("unroll") for (int k = 0; k < 2; ++k) dst[m][k] = *(const LAS bf16x8*)(lds + PG8_SA(b, h) + aoff + m * 2048 + k * 1024); } while (0)
; #define PG8_MMA(ai, bj, At, Bt) do { __builtin_amdgcn_s_setprio(1); _Pragma("unroll") for (int m = 0; m < 4; ++m) _Pragma("unroll") for (int n = 0; n < 2; ++n) _Pragma("unroll") for (int k = 0; k < 2; ++k) \
;         acc[ai][bj][m][n] = __builtin_amdgcn_mfma_f32_16x16x32_bf16(Bt[n][k], At[m][k], acc[ai][bj][m][n], 0, 0, 0); __builtin_amdgcn_s_setprio(0); } while (0)
; #define PG8_WAIT_V(n) asm volatile("s_waitcnt vmcnt(" #n ")" ::: "memory")
; #define PG8_WAIT_L(n) asm volatile("s_waitcnt lgkmcnt(" #n ")" ::: "memory")
; #define PG8_BAR __builtin_amdgcn_s_barrier()
; #define PG8_SCHED __builtin_amdgcn_sched_barrier(0)
; __device__ __forceinline__ void gemm_phase(const int tid, LAS unsigned char* lds, const Gemm g, const StaticOrder& S, const int mode  , void* Cout, const int ldc, float* rvs, const float* rbs, const float* rbs_tail) {
;     ...
;             PG8_WAIT_V(8); PG8_WAIT_L(0); PG8_BAR; PG8_MMA(0, 0, At, B0); PG8_MMA(0, 1, At, B1); PG8_BAR; PG8_SCHED;
;             PG8_LDA(At, 1, 1); PG8_STAGE(PG8_SB(1, 0), b3, voffB); PG8_STAGE(PG8_SB(1, 1), b3 + hstepB, voffB); PG8_STAGE(PG8_SA(1, 0), a3, voffA);
;             PG8_WAIT_V(8); PG8_WAIT_L(0); PG8_BAR; PG8_MMA(1, 0, At, B0); PG8_MMA(1, 1, At, B1); PG8_BAR; PG8_SCHED;
;         }
	s_setprio 0
	s_add_i32 s62, s68, s70
	v_lshl_add_u64 v[158:159], v[158:159], 0, s[36:37]
	s_mov_b32 m0, s62
	ds_read_b128 v[188:191], v149 offset:49152
	ds_read_b128 v[212:215], v149 offset:50176
	ds_read_b128 v[216:219], v149 offset:51200
	ds_read_b128 v[220:223], v149 offset:52224
	ds_read_b128 v[224:227], v149 offset:53248
	ds_read_b128 v[228:231], v149 offset:54272
	ds_read_b128 v[232:235], v149 offset:55296
	ds_read_b128 v[236:239], v149 offset:56320
	global_load_lds_dwordx4 v[158:159], off
	v_lshl_add_u64 v[158:159], v[192:193], 0, s[36:37]
	s_add_i32 m0, s62, 0x2000
	s_add_i32 s62, s73, s70
	global_load_lds_dwordx4 v[158:159], off
	v_lshl_add_u64 v[158:159], v[194:195], 0, s[36:37]
	s_mov_b32 m0, s62
	s_nop 0
	global_load_lds_dwordx4 v[158:159], off
	v_lshl_add_u64 v[158:159], v[240:241], 0, s[36:37]
	s_add_i32 m0, s62, 0x2000
	s_nop 0
	global_load_lds_dwordx4 v[158:159], off
	v_lshl_add_u64 v[158:159], v[242:243], 0, s[36:37]
	s_mov_b32 m0, s91
	s_nop 0
	global_load_lds_dwordx4 v[158:159], off
	v_lshl_add_u64 v[158:159], v[244:245], 0, s[36:37]
	s_mov_b32 m0, s16
	s_nop 0
	global_load_lds_dwordx4 v[158:159], off
	s_setprio 1
	s_waitcnt vmcnt(8)
	s_waitcnt lgkmcnt(0)
	s_barrier
	s_waitcnt lgkmcnt(0)
	v_mfma_f32_16x16x32_bf16 v[60:63], v[142:145], v[188:191], v[60:63]
	v_mfma_f32_16x16x32_bf16 v[56:59], v[154:157], v[188:191], v[56:59]
	v_mfma_f32_16x16x32_bf16 v[52:55], v[142:145], v[216:219], v[52:55]
	v_mfma_f32_16x16x32_bf16 v[48:51], v[154:157], v[216:219], v[48:51]
	v_mfma_f32_16x16x32_bf16 v[36:39], v[142:145], v[224:227], v[36:39]
	v_mfma_f32_16x16x32_bf16 v[32:35], v[154:157], v[224:227], v[32:35]
	v_mfma_f32_16x16x32_bf16 v[20:23], v[142:145], v[232:235], v[20:23]
	v_mfma_f32_16x16x32_bf16 v[16:19], v[154:157], v[232:235], v[16:19]
	v_mfma_f32_16x16x32_bf16 v[60:63], v[150:153], v[212:215], v[60:63]
	v_mfma_f32_16x16x32_bf16 v[56:59], v[168:171], v[212:215], v[56:59]
	v_mfma_f32_16x16x32_bf16 v[52:55], v[150:153], v[220:223], v[52:55]
	v_mfma_f32_16x16x32_bf16 v[48:51], v[168:171], v[220:223], v[48:51]
	v_mfma_f32_16x16x32_bf16 v[36:39], v[150:153], v[228:231], v[36:39]
	v_mfma_f32_16x16x32_bf16 v[32:35], v[168:171], v[228:231], v[32:35]
	v_mfma_f32_16x16x32_bf16 v[20:23], v[150:153], v[236:239], v[20:23]
	v_mfma_f32_16x16x32_bf16 v[16:19], v[168:171], v[236:239], v[16:19]
	s_setprio 0
	s_setprio 1
	v_mfma_f32_16x16x32_bf16 v[44:47], v[172:175], v[188:191], v[44:47]
	v_mfma_f32_16x16x32_bf16 v[40:43], v[180:183], v[188:191], v[40:43]
	v_mfma_f32_16x16x32_bf16 v[28:31], v[172:175], v[216:219], v[28:31]
	v_mfma_f32_16x16x32_bf16 v[24:27], v[180:183], v[216:219], v[24:27]
	v_mfma_f32_16x16x32_bf16 v[12:15], v[172:175], v[224:227], v[12:15]
	v_mfma_f32_16x16x32_bf16 v[8:11], v[180:183], v[224:227], v[8:11]
	v_mfma_f32_16x16x32_bf16 v[4:7], v[172:175], v[232:235], v[4:7]
	v_mfma_f32_16x16x32_bf16 v[0:3], v[180:183], v[232:235], v[0:3]
	v_mfma_f32_16x16x32_bf16 v[44:47], v[176:179], v[212:215], v[44:47]
	v_mfma_f32_16x16x32_bf16 v[40:43], v[184:187], v[212:215], v[40:43]
	v_mfma_f32_16x16x32_bf16 v[28:31], v[176:179], v[220:223], v[28:31]
	v_mfma_f32_16x16x32_bf16 v[24:27], v[184:187], v[220:223], v[24:27]
	v_mfma_f32_16x16x32_bf16 v[12:15], v[176:179], v[228:231], v[12:15]
	v_mfma_f32_16x16x32_bf16 v[8:11], v[184:187], v[228:231], v[8:11]
	v_mfma_f32_16x16x32_bf16 v[4:7], v[176:179], v[236:239], v[4:7]
	v_mfma_f32_16x16x32_bf16 v[0:3], v[184:187], v[236:239], v[0:3]
	s_barrier
	s_setprio 0
	s_add_u32 s60, s60, 0x100
	s_addc_u32 s61, s61, 0
	s_add_u32 s45, s45, 0x100
	s_addc_u32 s53, s53, 0
	s_cmp_ge_u32 s72, s3
	s_mov_b32 s68, s72
	s_cbranch_scc0 .LBB0_231
	s_branch .Lgemm_k_done

; #define PG8_BAR __builtin_amdgcn_s_barrier()
; __device__ __forceinline__ void gemm_phase(const int tid, LAS unsigned char* lds, const Gemm g, const StaticOrder& S, const int mode  , void* Cout, const int ldc, float* rvs, const float* rbs, const float* rbs_tail) {
;     ...
;         if (wr == 1) PG8_BAR;
.LBB0_269:
	s_andn2_b64 vcc, exec, s[92:93]
	s_cbranch_vccnz .LBB0_212
	s_branch .LBB0_212
